# SwiGLU (FFI) GEMM epilogue rewritten by hand with packed f32 ops on independent pairs (same per-element op order)
# speedup vs baseline: 1.0107x; 1.0107x over previous
; #define G_STAGE(bufoff, gbase, o0, h64) do { \
;         __builtin_amdgcn_global_load_lds((const unsigned*)((const char*)(gbase) + (o0)), (LAS unsigned*)(lds + (bufoff) + ldsw), 16, 0, 0); \
;         __builtin_amdgcn_global_load_lds((const unsigned*)((const char*)(gbase) + (h64) + (o0)), (LAS unsigned*)(lds + (bufoff) + ldsw + 8192), 16, 0, 0); } while (0)
; #define G_LDA(dst, b, h) do { _Pragma("unroll") for (int m = 0; m < 4; ++m) _Pragma("unroll") for (int k = 0; k < 2; ++k) dst[m][k] = *(const LAS bf16x8*)(lds + G_SA(b, h) + aoff + m * 2048 + k * 1024); } while (0)
; #define G_LDB(dst, b, h) do { _Pragma("unroll") for (int n = 0; n < 2; ++n) _Pragma("unroll") for (int k = 0; k < 2; ++k) dst[n][k] = *(const LAS bf16x8*)(lds + G_SB(b, h) + boff + n * 2048 + k * 1024); } while (0)
; #define G_WAIT_L(n) asm volatile("s_waitcnt lgkmcnt(" #n ")" ::: "memory")
; #define G_BAR __builtin_amdgcn_s_barrier()
; #define G_SCHED __builtin_amdgcn_sched_barrier(0)
;     ...
;         for (int t = 0; t < nt; t += 2) {
;             const bool last = (t == nt - 2);
;             const char* a1 = cA + (size_t)(t + 1) * ckA;
;             const char* a2 = last ? nA : cA + (size_t)(t + 2) * ckA; const char* b2 = last ? nB : cB + (size_t)(t + 2) * kB;
;             const char* a3 = a2 + ckA; const char* b3 = b2 + kB;
;             G_LDB(B0, 0, 0); G_SCHED; G_LDA(At, 0, 0); G_STAGE(G_SA(1, 1), a1 + chA, cA0, qA);
;             G_WAIT_L(8); G_BAR; G_WAIT_L(0); G_MMA(0, 0, At, B0); G_BAR; G_SCHED;
;             G_LDB(B1, 0, 1); G_STAGE(G_SB(0, 0), b2, cB0, qB);
;             G_BAR; G_WAIT_L(0); G_MMA(0, 1, At, B1); G_BAR;
;             G_LDA(At, 0, 1); G_STAGE(G_SA(0, 0), a2, cA0, qA);
;             G_BAR; G_WAIT_L(0); G_MMA(1, 0, At, B0); G_BAR; G_SCHED;
.LBB0_1120:
	s_add_u32 s4, s2, 0xfffc0080
	s_addc_u32 s5, s3, -1
	s_add_i32 s19, 0, 0x10000
	v_add_u32_e32 v0, s19, v149
	ds_read_b128 v[140:143], v0
	ds_read_b128 v[144:147], v0 offset:1024
	ds_read_b128 v[152:155], v0 offset:2048
	ds_read_b128 v[156:159], v0 offset:3072
	s_cmp_eq_u32 s18, 12
	s_cselect_b32 s5, s13, s5
	s_cselect_b32 s4, s12, s4
	s_cselect_b32 s41, s15, s17
	s_cselect_b32 s40, s14, s16
	v_lshl_add_u64 v[184:185], s[2:3], 0, v[138:139]
	s_add_i32 m0, s26, 0xc000
	ds_read_b128 v[160:163], v150
	ds_read_b128 v[164:167], v150 offset:1024
	ds_read_b128 v[172:175], v150 offset:2048
	ds_read_b128 v[176:179], v150 offset:3072
	ds_read_b128 v[180:183], v150 offset:4096
	ds_read_b128 v[196:199], v150 offset:5120
	ds_read_b128 v[200:203], v150 offset:6144
	ds_read_b128 v[204:207], v150 offset:7168
	global_load_lds_dwordx4 v[184:185], off
	v_lshl_add_u64 v[184:185], v[184:185], 0, s[0:1]
	s_add_i32 m0, s26, 0xe000
	s_nop 0
	global_load_lds_dwordx4 v[184:185], off
	s_waitcnt lgkmcnt(8)
	s_barrier
	s_waitcnt lgkmcnt(0)
	s_setprio 3
	s_waitcnt lgkmcnt(0)
	v_mfma_f32_16x16x32_bf16 v[132:135], v[140:143], v[160:163], v[132:135]
	v_mfma_f32_16x16x32_bf16 v[124:127], v[152:155], v[160:163], v[124:127]
	v_mfma_f32_16x16x32_bf16 v[116:119], v[140:143], v[172:175], v[116:119]
	v_mfma_f32_16x16x32_bf16 v[108:111], v[152:155], v[172:175], v[108:111]
	v_mfma_f32_16x16x32_bf16 v[100:103], v[140:143], v[180:183], v[100:103]
	v_mfma_f32_16x16x32_bf16 v[92:95], v[152:155], v[180:183], v[92:95]
	v_mfma_f32_16x16x32_bf16 v[84:87], v[140:143], v[200:203], v[84:87]
	v_mfma_f32_16x16x32_bf16 v[76:79], v[152:155], v[200:203], v[76:79]
	v_mfma_f32_16x16x32_bf16 v[132:135], v[144:147], v[164:167], v[132:135]
	v_mfma_f32_16x16x32_bf16 v[124:127], v[156:159], v[164:167], v[124:127]
	v_mfma_f32_16x16x32_bf16 v[116:119], v[144:147], v[176:179], v[116:119]
	v_mfma_f32_16x16x32_bf16 v[108:111], v[156:159], v[176:179], v[108:111]
	v_mfma_f32_16x16x32_bf16 v[100:103], v[144:147], v[196:199], v[100:103]
	v_mfma_f32_16x16x32_bf16 v[92:95], v[156:159], v[196:199], v[92:95]
	v_mfma_f32_16x16x32_bf16 v[84:87], v[144:147], v[204:207], v[84:87]
	v_mfma_f32_16x16x32_bf16 v[76:79], v[156:159], v[204:207], v[76:79]
	s_setprio 0
	s_barrier
	s_add_i32 s39, 0, 0x14000
	s_add_i32 s19, s19, s21
	v_add_u32_e32 v0, s39, v149
	v_lshl_add_u64 v[184:185], s[40:41], 0, v[2:3]
	s_mov_b32 m0, s19
	ds_read_b128 v[208:211], v0
	ds_read_b128 v[212:215], v0 offset:1024
	ds_read_b128 v[216:219], v0 offset:2048
	ds_read_b128 v[220:223], v0 offset:3072
	global_load_lds_dwordx4 v[184:185], off
	v_lshl_add_u64 v[224:225], v[184:185], 0, s[0:1]
	s_add_i32 m0, s19, 0x2000
	s_nop 0
	global_load_lds_dwordx4 v[224:225], off
	s_barrier
	s_waitcnt lgkmcnt(0)
	s_setprio 3
	s_waitcnt lgkmcnt(0)
	v_mfma_f32_16x16x32_bf16 v[128:131], v[208:211], v[160:163], v[128:131]
	v_mfma_f32_16x16x32_bf16 v[120:123], v[216:219], v[160:163], v[120:123]
	v_mfma_f32_16x16x32_bf16 v[112:115], v[208:211], v[172:175], v[112:115]
	v_mfma_f32_16x16x32_bf16 v[104:107], v[216:219], v[172:175], v[104:107]
	v_mfma_f32_16x16x32_bf16 v[96:99], v[208:211], v[180:183], v[96:99]
	v_mfma_f32_16x16x32_bf16 v[88:91], v[216:219], v[180:183], v[88:91]
	v_mfma_f32_16x16x32_bf16 v[80:83], v[208:211], v[200:203], v[80:83]
	v_mfma_f32_16x16x32_bf16 v[72:75], v[216:219], v[200:203], v[72:75]
	v_mfma_f32_16x16x32_bf16 v[128:131], v[212:215], v[164:167], v[128:131]
	v_mfma_f32_16x16x32_bf16 v[120:123], v[220:223], v[164:167], v[120:123]
	v_mfma_f32_16x16x32_bf16 v[112:115], v[212:215], v[176:179], v[112:115]
	v_mfma_f32_16x16x32_bf16 v[104:107], v[220:223], v[176:179], v[104:107]
	v_mfma_f32_16x16x32_bf16 v[96:99], v[212:215], v[196:199], v[96:99]
	v_mfma_f32_16x16x32_bf16 v[88:91], v[220:223], v[196:199], v[88:91]
	v_mfma_f32_16x16x32_bf16 v[80:83], v[212:215], v[204:207], v[80:83]
	v_mfma_f32_16x16x32_bf16 v[72:75], v[220:223], v[204:207], v[72:75]
	s_setprio 0
	s_mov_b32 m0, s26
	v_lshl_add_u64 v[224:225], s[4:5], 0, v[136:137]
	s_barrier
	ds_read_b128 v[160:163], v150 offset:16384
	ds_read_b128 v[164:167], v150 offset:17408
	ds_read_b128 v[172:175], v150 offset:18432
	ds_read_b128 v[176:179], v150 offset:19456
	ds_read_b128 v[180:183], v150 offset:20480
	ds_read_b128 v[196:199], v150 offset:21504
	ds_read_b128 v[200:203], v150 offset:22528
	ds_read_b128 v[204:207], v150 offset:23552
	global_load_lds_dwordx4 v[224:225], off
	v_lshl_add_u64 v[226:227], v[224:225], 0, s[0:1]
	s_mov_b32 m0, s27
	s_nop 0
	global_load_lds_dwordx4 v[226:227], off
	s_barrier
	s_waitcnt lgkmcnt(0)
	s_setprio 3
	s_waitcnt lgkmcnt(0)
	v_mfma_f32_16x16x32_bf16 v[68:71], v[140:143], v[160:163], v[68:71]
	v_mfma_f32_16x16x32_bf16 v[60:63], v[152:155], v[160:163], v[60:63]
	v_mfma_f32_16x16x32_bf16 v[52:55], v[140:143], v[172:175], v[52:55]
	v_mfma_f32_16x16x32_bf16 v[44:47], v[152:155], v[172:175], v[44:47]
	v_mfma_f32_16x16x32_bf16 v[36:39], v[140:143], v[180:183], v[36:39]
	v_mfma_f32_16x16x32_bf16 v[28:31], v[152:155], v[180:183], v[28:31]
	v_mfma_f32_16x16x32_bf16 v[20:23], v[140:143], v[200:203], v[20:23]
	v_mfma_f32_16x16x32_bf16 v[12:15], v[152:155], v[200:203], v[12:15]
	v_mfma_f32_16x16x32_bf16 v[68:71], v[144:147], v[164:167], v[68:71]
	v_mfma_f32_16x16x32_bf16 v[60:63], v[156:159], v[164:167], v[60:63]
	v_mfma_f32_16x16x32_bf16 v[52:55], v[144:147], v[176:179], v[52:55]
	v_mfma_f32_16x16x32_bf16 v[44:47], v[156:159], v[176:179], v[44:47]
	v_mfma_f32_16x16x32_bf16 v[36:39], v[144:147], v[196:199], v[36:39]
	v_mfma_f32_16x16x32_bf16 v[28:31], v[156:159], v[196:199], v[28:31]
	v_mfma_f32_16x16x32_bf16 v[20:23], v[144:147], v[204:207], v[20:23]
	v_mfma_f32_16x16x32_bf16 v[12:15], v[156:159], v[204:207], v[12:15]
	s_setprio 0
	s_barrier
; #define G_STAGE(bufoff, gbase, o0, h64) do { \
;         __builtin_amdgcn_global_load_lds((const unsigned*)((const char*)(gbase) + (o0)), (LAS unsigned*)(lds + (bufoff) + ldsw), 16, 0, 0); \
;         __builtin_amdgcn_global_load_lds((const unsigned*)((const char*)(gbase) + (h64) + (o0)), (LAS unsigned*)(lds + (bufoff) + ldsw + 8192), 16, 0, 0); } while (0)
; #define G_LDA(dst, b, h) do { _Pragma("unroll") for (int m = 0; m < 4; ++m) _Pragma("unroll") for (int k = 0; k < 2; ++k) dst[m][k] = *(const LAS bf16x8*)(lds + G_SA(b, h) + aoff + m * 2048 + k * 1024); } while (0)
; #define G_LDB(dst, b, h) do { _Pragma("unroll") for (int n = 0; n < 2; ++n) _Pragma("unroll") for (int k = 0; k < 2; ++k) dst[n][k] = *(const LAS bf16x8*)(lds + G_SB(b, h) + boff + n * 2048 + k * 1024); } while (0)
; #define G_WAIT_V(n) asm volatile("s_waitcnt vmcnt(" #n ")" ::: "memory")
; #define G_WAIT_L(n) asm volatile("s_waitcnt lgkmcnt(" #n ")" ::: "memory")
; #define G_BAR __builtin_amdgcn_s_barrier()
; #define G_SCHED __builtin_amdgcn_sched_barrier(0)
;     ...
;             G_BAR; G_WAIT_L(0); G_MMA(1, 0, At, B0); G_BAR; G_SCHED;
;             G_STAGE(G_SB(0, 1), b2 + chB, cB0, qB);
;             G_WAIT_V(6); G_BAR; G_MMA(1, 1, At, B1); G_BAR;
;             G_LDB(B0, 1, 0); G_SCHED; G_LDA(At, 1, 0); G_STAGE(G_SA(0, 1), a2 + chA, cA0, qA);
;             G_WAIT_L(8); G_BAR; G_WAIT_L(0); G_MMA(0, 0, At, B0); G_BAR; G_SCHED;
;             G_LDB(B1, 1, 1); G_STAGE(G_SB(1, 0), b3, cB0, qB);
;             G_BAR; G_WAIT_L(0); G_MMA(0, 1, At, B1); G_BAR;
;             G_LDA(At, 1, 1); G_STAGE(G_SA(1, 0), a3, cA0, qA);
;             G_BAR; G_WAIT_L(0); G_MMA(1, 0, At, B0); G_BAR; G_SCHED;
	s_add_i32 s4, s39, s21
	v_lshl_add_u64 v[140:141], v[184:185], 0, s[42:43]
	s_mov_b32 m0, s4
	s_nop 0
	global_load_lds_dwordx4 v[140:141], off
	v_lshl_add_u64 v[140:141], v[184:185], 0, s[50:51]
	s_add_i32 m0, s4, 0x2000
	s_nop 0
	global_load_lds_dwordx4 v[140:141], off
	s_waitcnt vmcnt(6)
	s_barrier
	s_setprio 3
	v_mfma_f32_16x16x32_bf16 v[64:67], v[208:211], v[160:163], v[64:67]
	v_mfma_f32_16x16x32_bf16 v[56:59], v[216:219], v[160:163], v[56:59]
	v_mfma_f32_16x16x32_bf16 v[48:51], v[208:211], v[172:175], v[48:51]
	v_mfma_f32_16x16x32_bf16 v[40:43], v[216:219], v[172:175], v[40:43]
	v_mfma_f32_16x16x32_bf16 v[32:35], v[208:211], v[180:183], v[32:35]
	v_mfma_f32_16x16x32_bf16 v[24:27], v[216:219], v[180:183], v[24:27]
	v_mfma_f32_16x16x32_bf16 v[16:19], v[208:211], v[200:203], v[16:19]
	v_mfma_f32_16x16x32_bf16 v[8:11], v[216:219], v[200:203], v[8:11]
	v_mfma_f32_16x16x32_bf16 v[64:67], v[212:215], v[164:167], v[64:67]
	v_mfma_f32_16x16x32_bf16 v[56:59], v[220:223], v[164:167], v[56:59]
	v_mfma_f32_16x16x32_bf16 v[48:51], v[212:215], v[176:179], v[48:51]
	v_mfma_f32_16x16x32_bf16 v[40:43], v[220:223], v[176:179], v[40:43]
	v_mfma_f32_16x16x32_bf16 v[32:35], v[212:215], v[196:199], v[32:35]
	v_mfma_f32_16x16x32_bf16 v[24:27], v[220:223], v[196:199], v[24:27]
	v_mfma_f32_16x16x32_bf16 v[16:19], v[212:215], v[204:207], v[16:19]
	v_mfma_f32_16x16x32_bf16 v[8:11], v[220:223], v[204:207], v[8:11]
	s_setprio 0
	s_add_i32 s4, 0, 0x18000
	v_add_u32_e32 v0, s4, v149
	s_barrier
	ds_read_b128 v[140:143], v0
	ds_read_b128 v[144:147], v0 offset:1024
	ds_read_b128 v[152:155], v0 offset:2048
	ds_read_b128 v[156:159], v0 offset:3072
	s_mov_b32 m0, s29
	v_lshl_add_u64 v[208:209], v[224:225], 0, s[42:43]
	ds_read_b128 v[160:163], v150 offset:32768
	ds_read_b128 v[164:167], v150 offset:33792
	ds_read_b128 v[172:175], v150 offset:34816
	ds_read_b128 v[176:179], v150 offset:35840
	ds_read_b128 v[180:183], v150 offset:36864
	ds_read_b128 v[196:199], v150 offset:37888
	ds_read_b128 v[200:203], v150 offset:38912
	ds_read_b128 v[204:207], v150 offset:39936
	global_load_lds_dwordx4 v[208:209], off
	v_lshl_add_u64 v[208:209], v[224:225], 0, s[50:51]
	s_mov_b32 m0, s30
	s_nop 0
	global_load_lds_dwordx4 v[208:209], off
	s_waitcnt lgkmcnt(8)
	s_barrier
	s_waitcnt lgkmcnt(0)
	s_setprio 3
	s_waitcnt lgkmcnt(0)
	v_mfma_f32_16x16x32_bf16 v[132:135], v[140:143], v[160:163], v[132:135]
	v_mfma_f32_16x16x32_bf16 v[124:127], v[152:155], v[160:163], v[124:127]
	v_mfma_f32_16x16x32_bf16 v[116:119], v[140:143], v[172:175], v[116:119]
	v_mfma_f32_16x16x32_bf16 v[108:111], v[152:155], v[172:175], v[108:111]
	v_mfma_f32_16x16x32_bf16 v[100:103], v[140:143], v[180:183], v[100:103]
	v_mfma_f32_16x16x32_bf16 v[92:95], v[152:155], v[180:183], v[92:95]
	v_mfma_f32_16x16x32_bf16 v[84:87], v[140:143], v[200:203], v[84:87]
	v_mfma_f32_16x16x32_bf16 v[76:79], v[152:155], v[200:203], v[76:79]
	v_mfma_f32_16x16x32_bf16 v[132:135], v[144:147], v[164:167], v[132:135]
	v_mfma_f32_16x16x32_bf16 v[124:127], v[156:159], v[164:167], v[124:127]
	v_mfma_f32_16x16x32_bf16 v[116:119], v[144:147], v[176:179], v[116:119]
	v_mfma_f32_16x16x32_bf16 v[108:111], v[156:159], v[176:179], v[108:111]
	v_mfma_f32_16x16x32_bf16 v[100:103], v[144:147], v[196:199], v[100:103]
	v_mfma_f32_16x16x32_bf16 v[92:95], v[156:159], v[196:199], v[92:95]
	v_mfma_f32_16x16x32_bf16 v[84:87], v[144:147], v[204:207], v[84:87]
	v_mfma_f32_16x16x32_bf16 v[76:79], v[156:159], v[204:207], v[76:79]
	s_setprio 0
	s_barrier
	s_add_i32 s5, 0, 0x1c000
	s_add_i32 s4, s4, s21
	v_add_u32_e32 v0, s5, v149
	v_lshl_add_u64 v[226:227], v[184:185], 0, s[46:47]
	s_mov_b32 m0, s4
	ds_read_b128 v[208:211], v0
	ds_read_b128 v[212:215], v0 offset:1024
	ds_read_b128 v[216:219], v0 offset:2048
	ds_read_b128 v[220:223], v0 offset:3072
	global_load_lds_dwordx4 v[226:227], off
	v_lshl_add_u64 v[226:227], v[184:185], 0, s[52:53]
	s_add_i32 m0, s4, 0x2000
	s_nop 0
	global_load_lds_dwordx4 v[226:227], off
	s_barrier
	s_waitcnt lgkmcnt(0)
	s_setprio 3
	s_waitcnt lgkmcnt(0)
	v_mfma_f32_16x16x32_bf16 v[128:131], v[208:211], v[160:163], v[128:131]
	v_mfma_f32_16x16x32_bf16 v[120:123], v[216:219], v[160:163], v[120:123]
	v_mfma_f32_16x16x32_bf16 v[112:115], v[208:211], v[172:175], v[112:115]
	v_mfma_f32_16x16x32_bf16 v[104:107], v[216:219], v[172:175], v[104:107]
	v_mfma_f32_16x16x32_bf16 v[96:99], v[208:211], v[180:183], v[96:99]
	v_mfma_f32_16x16x32_bf16 v[88:91], v[216:219], v[180:183], v[88:91]
	v_mfma_f32_16x16x32_bf16 v[80:83], v[208:211], v[200:203], v[80:83]
	v_mfma_f32_16x16x32_bf16 v[72:75], v[216:219], v[200:203], v[72:75]
	v_mfma_f32_16x16x32_bf16 v[128:131], v[212:215], v[164:167], v[128:131]
	v_mfma_f32_16x16x32_bf16 v[120:123], v[220:223], v[164:167], v[120:123]
	v_mfma_f32_16x16x32_bf16 v[112:115], v[212:215], v[176:179], v[112:115]
	v_mfma_f32_16x16x32_bf16 v[104:107], v[220:223], v[176:179], v[104:107]
	v_mfma_f32_16x16x32_bf16 v[96:99], v[212:215], v[196:199], v[96:99]
	v_mfma_f32_16x16x32_bf16 v[88:91], v[220:223], v[196:199], v[88:91]
	v_mfma_f32_16x16x32_bf16 v[80:83], v[212:215], v[204:207], v[80:83]
	v_mfma_f32_16x16x32_bf16 v[72:75], v[220:223], v[204:207], v[72:75]
	s_setprio 0
	s_mov_b32 m0, s31
	v_lshl_add_u64 v[226:227], v[224:225], 0, s[46:47]
	s_barrier
	ds_read_b128 v[160:163], v150 offset:49152
	ds_read_b128 v[164:167], v150 offset:50176
	ds_read_b128 v[172:175], v150 offset:51200
	ds_read_b128 v[176:179], v150 offset:52224
	ds_read_b128 v[180:183], v150 offset:53248
	ds_read_b128 v[196:199], v150 offset:54272
	ds_read_b128 v[200:203], v150 offset:55296
	ds_read_b128 v[204:207], v150 offset:56320
	global_load_lds_dwordx4 v[226:227], off
	v_lshl_add_u64 v[224:225], v[224:225], 0, s[52:53]
	s_mov_b32 m0, s34
	s_nop 0
	global_load_lds_dwordx4 v[224:225], off
	s_barrier
; __device__ __forceinline__ float sigmoidf_(float v) { return __builtin_amdgcn_rcpf(1.0f + __expf(-v)); }
; __device__ __forceinline__ u32x4 pack8(const f32x4 a, const f32x4 b) { u32x4 w; w.x = cvt_pk_bf16(a[0], a[1]); w.y = cvt_pk_bf16(a[2], a[3]); w.z = cvt_pk_bf16(b[0], b[1]); w.w = cvt_pk_bf16(b[2], b[3]); return w; }
; #define MEMFENCE asm volatile("" ::: "memory")
; #define G_STAGE(bufoff, gbase, o0, h64) do { \
;         __builtin_amdgcn_global_load_lds((const unsigned*)((const char*)(gbase) + (o0)), (LAS unsigned*)(lds + (bufoff) + ldsw), 16, 0, 0); \
;         __builtin_amdgcn_global_load_lds((const unsigned*)((const char*)(gbase) + (h64) + (o0)), (LAS unsigned*)(lds + (bufoff) + ldsw + 8192), 16, 0, 0); } while (0)
; #define G_WAIT_V(n) asm volatile("s_waitcnt vmcnt(" #n ")" ::: "memory")
; #define G_WAIT_L(n) asm volatile("s_waitcnt lgkmcnt(" #n ")" ::: "memory")
; #define G_BAR __builtin_amdgcn_s_barrier()
; #define G_SCHED __builtin_amdgcn_sched_barrier(0)
;     template <int KIND> __device__ __forceinline__ void run(f32x4 (&acc)[2][2][4][2], const Unit& u, int tid_in) const {
;     ...
;         if constexpr (KIND == K_FFI) { bf16_t* act = zb; float rs[8]; get_rs(u, wr, fr, rs);
; #pragma unroll
;             for (int ai = 0; ai < 2; ++ai)
; #pragma unroll
;                 for (int m = 0; m < 4; ++m) { int row = rbase + ai * 128 + m * 16; asm volatile("" : "+v"(row)); const float r = rs[ai * 4 + m]; f32x4 o[2];
; #pragma unroll
;                     for (int n = 0; n < 2; ++n) { const f32x4 g = acc[ai][0][m][n] * r, v = acc[ai][1][m][n] * r;
; #pragma unroll
;                         for (int j = 0; j < 4; ++j) o[n][j] = g[j] * sigmoidf_(g[j]) * v[j]; }
;                     *(u32x4*)(act + (size_t)row * ZW + u.pn * 128 + cl) = pack8(o[0], o[1]); MEMFENCE; }
;     ...
;             G_BAR; G_WAIT_L(0); G_MMA(1, 0, At, B0); G_BAR; G_SCHED;
;             G_STAGE(G_SB(1, 1), b3 + chB, cB0, qB);
;             G_WAIT_V(6); G_BAR; G_MMA(1, 1, At, B1); G_BAR;
;         }
;         E.template run<cs.kind>(acc, cur, tid);
	s_waitcnt lgkmcnt(0)
	s_setprio 3
	s_waitcnt lgkmcnt(0)
	v_mfma_f32_16x16x32_bf16 v[68:71], v[140:143], v[160:163], v[68:71]
	v_mfma_f32_16x16x32_bf16 v[60:63], v[152:155], v[160:163], v[60:63]
	v_mfma_f32_16x16x32_bf16 v[52:55], v[140:143], v[172:175], v[52:55]
	v_mfma_f32_16x16x32_bf16 v[44:47], v[152:155], v[172:175], v[44:47]
	v_mfma_f32_16x16x32_bf16 v[36:39], v[140:143], v[180:183], v[36:39]
	v_mfma_f32_16x16x32_bf16 v[28:31], v[152:155], v[180:183], v[28:31]
	v_mfma_f32_16x16x32_bf16 v[20:23], v[140:143], v[200:203], v[20:23]
	v_mfma_f32_16x16x32_bf16 v[12:15], v[152:155], v[200:203], v[12:15]
	v_mfma_f32_16x16x32_bf16 v[68:71], v[144:147], v[164:167], v[68:71]
	v_mfma_f32_16x16x32_bf16 v[60:63], v[156:159], v[164:167], v[60:63]
	v_mfma_f32_16x16x32_bf16 v[52:55], v[144:147], v[176:179], v[52:55]
	v_mfma_f32_16x16x32_bf16 v[44:47], v[156:159], v[176:179], v[44:47]
	v_mfma_f32_16x16x32_bf16 v[36:39], v[144:147], v[196:199], v[36:39]
	v_mfma_f32_16x16x32_bf16 v[28:31], v[156:159], v[196:199], v[28:31]
	v_mfma_f32_16x16x32_bf16 v[20:23], v[144:147], v[204:207], v[20:23]
	v_mfma_f32_16x16x32_bf16 v[12:15], v[156:159], v[204:207], v[12:15]
	s_setprio 0
	s_barrier
	s_add_i32 s4, s5, s21
	v_lshl_add_u64 v[140:141], v[184:185], 0, s[54:55]
	s_mov_b32 m0, s4
	s_nop 0
	global_load_lds_dwordx4 v[140:141], off
	v_lshl_add_u64 v[140:141], v[184:185], 0, s[58:59]
	s_add_i32 m0, s4, 0x2000
	s_nop 0
	global_load_lds_dwordx4 v[140:141], off
	s_waitcnt vmcnt(6)
	s_barrier
	s_setprio 3
	v_mfma_f32_16x16x32_bf16 v[64:67], v[208:211], v[160:163], v[64:67]
	v_mfma_f32_16x16x32_bf16 v[56:59], v[216:219], v[160:163], v[56:59]
	v_mfma_f32_16x16x32_bf16 v[48:51], v[208:211], v[172:175], v[48:51]
	v_mfma_f32_16x16x32_bf16 v[40:43], v[216:219], v[172:175], v[40:43]
	v_mfma_f32_16x16x32_bf16 v[32:35], v[208:211], v[180:183], v[32:35]
	v_mfma_f32_16x16x32_bf16 v[24:27], v[216:219], v[180:183], v[24:27]
	v_mfma_f32_16x16x32_bf16 v[16:19], v[208:211], v[200:203], v[16:19]
	v_mfma_f32_16x16x32_bf16 v[8:11], v[216:219], v[200:203], v[8:11]
	v_mfma_f32_16x16x32_bf16 v[64:67], v[212:215], v[164:167], v[64:67]
	v_mfma_f32_16x16x32_bf16 v[56:59], v[220:223], v[164:167], v[56:59]
	v_mfma_f32_16x16x32_bf16 v[48:51], v[212:215], v[176:179], v[48:51]
	v_mfma_f32_16x16x32_bf16 v[40:43], v[220:223], v[176:179], v[40:43]
	v_mfma_f32_16x16x32_bf16 v[32:35], v[212:215], v[196:199], v[32:35]
	v_mfma_f32_16x16x32_bf16 v[24:27], v[220:223], v[196:199], v[24:27]
	v_mfma_f32_16x16x32_bf16 v[16:19], v[212:215], v[204:207], v[16:19]
	v_mfma_f32_16x16x32_bf16 v[8:11], v[220:223], v[204:207], v[8:11]
	s_setprio 0
	s_add_i32 s18, s18, 2
	s_add_u32 s2, s2, 0x100
	s_addc_u32 s3, s3, 0
	s_add_u32 s16, s16, 0x100
	s_addc_u32 s17, s17, 0
	s_cmp_gt_u32 s18, 13
	s_barrier
	s_cbranch_scc0 .LBB0_1120
	v_readfirstlane_b32 s2, v148
	s_lshr_b32 s4, s2, 1
	s_and_b32 s4, s4, 0x60
	v_lshrrev_b32_e32 v0, 1, v148
	v_and_or_b32 v0, v0, 24, s4
	v_and_b32_e32 v140, 15, v148
	s_lshl_b32 s4, s38, 10
	s_and_b32 s3, s2, 0xffffff00
	s_add_i32 s4, s4, s3
	v_lshl_add_u32 v141, v140, 2, s4
	v_add_u32_e32 v141, 0x20010, v141
	ds_read_b32 v240, v141
	ds_read_b32 v242, v141 offset:64
	ds_read_b32 v244, v141 offset:128
	ds_read_b32 v246, v141 offset:192
	ds_read_b32 v248, v141 offset:512
	ds_read_b32 v250, v141 offset:576
	ds_read_b32 v252, v141 offset:640
	ds_read_b32 v254, v141 offset:704
	s_ashr_i32 s3, s2, 2
	s_andn2_b32 s3, s3, 63
	v_or_b32_e32 v140, s3, v140
	v_lshl_add_u32 v140, s37, 8, v140
	v_mul_lo_u32 v140, v140, s76
	s_lshl_b32 s3, s33, 8
	v_lshlrev_b32_e32 v0, 1, v0
	v_add3_u32 v140, v140, v0, s3
	s_mov_b64 s[4:5], s[6:7]
	s_mov_b32 s2, 0xbfb8aa3b
	s_mov_b32 s100, 1.0
	s_waitcnt lgkmcnt(0)
	v_pk_mul_f32 v[132:133], v[132:133], v[240:241] op_sel_hi:[1,0]
	v_pk_mul_f32 v[128:129], v[128:129], v[240:241] op_sel_hi:[1,0]
	v_pk_mul_f32 v[216:217], v[132:133], s[2:3] op_sel_hi:[1,0]
	v_pk_mul_f32 v[134:135], v[134:135], v[240:241] op_sel_hi:[1,0]
	v_pk_mul_f32 v[130:131], v[130:131], v[240:241] op_sel_hi:[1,0]
	v_pk_mul_f32 v[218:219], v[134:135], s[2:3] op_sel_hi:[1,0]
	v_pk_mul_f32 v[124:125], v[124:125], v[240:241] op_sel_hi:[1,0]
	v_pk_mul_f32 v[120:121], v[120:121], v[240:241] op_sel_hi:[1,0]
	v_pk_mul_f32 v[220:221], v[124:125], s[2:3] op_sel_hi:[1,0]
	v_pk_mul_f32 v[126:127], v[126:127], v[240:241] op_sel_hi:[1,0]
	v_pk_mul_f32 v[122:123], v[122:123], v[240:241] op_sel_hi:[1,0]
	v_pk_mul_f32 v[222:223], v[126:127], s[2:3] op_sel_hi:[1,0]
	v_exp_f32_e32 v216, v216
	v_exp_f32_e32 v217, v217
	v_exp_f32_e32 v218, v218
	v_exp_f32_e32 v219, v219
	v_exp_f32_e32 v220, v220
	v_exp_f32_e32 v221, v221
	v_exp_f32_e32 v222, v222
	v_exp_f32_e32 v223, v223
	v_pk_add_f32 v[216:217], v[216:217], s[100:101] op_sel_hi:[1,0]
	v_pk_add_f32 v[218:219], v[218:219], s[100:101] op_sel_hi:[1,0]
	v_pk_add_f32 v[220:221], v[220:221], s[100:101] op_sel_hi:[1,0]
	v_pk_add_f32 v[222:223], v[222:223], s[100:101] op_sel_hi:[1,0]
	v_rcp_f32_e32 v216, v216
	v_rcp_f32_e32 v217, v217
	v_rcp_f32_e32 v218, v218
	v_rcp_f32_e32 v219, v219
	v_rcp_f32_e32 v220, v220
	v_rcp_f32_e32 v221, v221
	v_rcp_f32_e32 v222, v222
	v_rcp_f32_e32 v223, v223
	v_pk_mul_f32 v[132:133], v[132:133], v[216:217]
	v_pk_mul_f32 v[134:135], v[134:135], v[218:219]
	v_pk_mul_f32 v[124:125], v[124:125], v[220:221]
	v_pk_mul_f32 v[126:127], v[126:127], v[222:223]
	v_pk_mul_f32 v[132:133], v[132:133], v[128:129]
	v_pk_mul_f32 v[134:135], v[134:135], v[130:131]
	v_pk_mul_f32 v[124:125], v[124:125], v[120:121]
	v_pk_mul_f32 v[126:127], v[126:127], v[122:123]
	v_cvt_pk_bf16_f32 v236, v132, v133
	v_cvt_pk_bf16_f32 v237, v134, v135
	v_cvt_pk_bf16_f32 v238, v124, v125
; __device__ __forceinline__ float sigmoidf_(float v) { return __builtin_amdgcn_rcpf(1.0f + __expf(-v)); }
; __device__ __forceinline__ u32x4 pack8(const f32x4 a, const f32x4 b) { u32x4 w; w.x = cvt_pk_bf16(a[0], a[1]); w.y = cvt_pk_bf16(a[2], a[3]); w.z = cvt_pk_bf16(b[0], b[1]); w.w = cvt_pk_bf16(b[2], b[3]); return w; }
; #define MEMFENCE asm volatile("" ::: "memory")
;     template <int KIND> __device__ __forceinline__ void run(f32x4 (&acc)[2][2][4][2], const Unit& u, int tid_in) const {
;     ...
;         if constexpr (KIND == K_FFI) { bf16_t* act = zb; float rs[8]; get_rs(u, wr, fr, rs);
; #pragma unroll
;             for (int ai = 0; ai < 2; ++ai)
; #pragma unroll
;                 for (int m = 0; m < 4; ++m) { int row = rbase + ai * 128 + m * 16; asm volatile("" : "+v"(row)); const float r = rs[ai * 4 + m]; f32x4 o[2];
; #pragma unroll
;                     for (int n = 0; n < 2; ++n) { const f32x4 g = acc[ai][0][m][n] * r, v = acc[ai][1][m][n] * r;
; #pragma unroll
;                         for (int j = 0; j < 4; ++j) o[n][j] = g[j] * sigmoidf_(g[j]) * v[j]; }
;                     *(u32x4*)(act + (size_t)row * ZW + u.pn * 128 + cl) = pack8(o[0], o[1]); MEMFENCE; }
	v_cvt_pk_bf16_f32 v239, v126, v127
	global_store_dwordx4 v140, v[236:239], s[4:5]
	s_add_u32 s4, s4, 0x16000
	s_addc_u32 s5, s5, 0
	v_pk_mul_f32 v[116:117], v[116:117], v[242:243] op_sel_hi:[1,0]
	v_pk_mul_f32 v[112:113], v[112:113], v[242:243] op_sel_hi:[1,0]
	v_pk_mul_f32 v[216:217], v[116:117], s[2:3] op_sel_hi:[1,0]
	v_pk_mul_f32 v[118:119], v[118:119], v[242:243] op_sel_hi:[1,0]
	v_pk_mul_f32 v[114:115], v[114:115], v[242:243] op_sel_hi:[1,0]
	v_pk_mul_f32 v[218:219], v[118:119], s[2:3] op_sel_hi:[1,0]
	v_pk_mul_f32 v[108:109], v[108:109], v[242:243] op_sel_hi:[1,0]
	v_pk_mul_f32 v[104:105], v[104:105], v[242:243] op_sel_hi:[1,0]
	v_pk_mul_f32 v[220:221], v[108:109], s[2:3] op_sel_hi:[1,0]
	v_pk_mul_f32 v[110:111], v[110:111], v[242:243] op_sel_hi:[1,0]
	v_pk_mul_f32 v[106:107], v[106:107], v[242:243] op_sel_hi:[1,0]
	v_pk_mul_f32 v[222:223], v[110:111], s[2:3] op_sel_hi:[1,0]
	v_exp_f32_e32 v216, v216
	v_exp_f32_e32 v217, v217
	v_exp_f32_e32 v218, v218
	v_exp_f32_e32 v219, v219
	v_exp_f32_e32 v220, v220
	v_exp_f32_e32 v221, v221
	v_exp_f32_e32 v222, v222
	v_exp_f32_e32 v223, v223
	v_pk_add_f32 v[216:217], v[216:217], s[100:101] op_sel_hi:[1,0]
	v_pk_add_f32 v[218:219], v[218:219], s[100:101] op_sel_hi:[1,0]
	v_pk_add_f32 v[220:221], v[220:221], s[100:101] op_sel_hi:[1,0]
	v_pk_add_f32 v[222:223], v[222:223], s[100:101] op_sel_hi:[1,0]
	v_rcp_f32_e32 v216, v216
	v_rcp_f32_e32 v217, v217
	v_rcp_f32_e32 v218, v218
	v_rcp_f32_e32 v219, v219
	v_rcp_f32_e32 v220, v220
	v_rcp_f32_e32 v221, v221
	v_rcp_f32_e32 v222, v222
	v_rcp_f32_e32 v223, v223
	v_pk_mul_f32 v[116:117], v[116:117], v[216:217]
	v_pk_mul_f32 v[118:119], v[118:119], v[218:219]
	v_pk_mul_f32 v[108:109], v[108:109], v[220:221]
	v_pk_mul_f32 v[110:111], v[110:111], v[222:223]
	v_pk_mul_f32 v[116:117], v[116:117], v[112:113]
	v_pk_mul_f32 v[118:119], v[118:119], v[114:115]
	v_pk_mul_f32 v[108:109], v[108:109], v[104:105]
	v_pk_mul_f32 v[110:111], v[110:111], v[106:107]
	v_cvt_pk_bf16_f32 v236, v116, v117
	v_cvt_pk_bf16_f32 v237, v118, v119
	v_cvt_pk_bf16_f32 v238, v108, v109
	v_cvt_pk_bf16_f32 v239, v110, v111
	global_store_dwordx4 v140, v[236:239], s[4:5]
	s_add_u32 s4, s4, 0x16000
	s_addc_u32 s5, s5, 0
	v_pk_mul_f32 v[100:101], v[100:101], v[244:245] op_sel_hi:[1,0]
	v_pk_mul_f32 v[96:97], v[96:97], v[244:245] op_sel_hi:[1,0]
	v_pk_mul_f32 v[216:217], v[100:101], s[2:3] op_sel_hi:[1,0]
	v_pk_mul_f32 v[102:103], v[102:103], v[244:245] op_sel_hi:[1,0]
	v_pk_mul_f32 v[98:99], v[98:99], v[244:245] op_sel_hi:[1,0]
	v_pk_mul_f32 v[218:219], v[102:103], s[2:3] op_sel_hi:[1,0]
	v_pk_mul_f32 v[92:93], v[92:93], v[244:245] op_sel_hi:[1,0]
	v_pk_mul_f32 v[88:89], v[88:89], v[244:245] op_sel_hi:[1,0]
	v_pk_mul_f32 v[220:221], v[92:93], s[2:3] op_sel_hi:[1,0]
	v_pk_mul_f32 v[94:95], v[94:95], v[244:245] op_sel_hi:[1,0]
	v_pk_mul_f32 v[90:91], v[90:91], v[244:245] op_sel_hi:[1,0]
	v_pk_mul_f32 v[222:223], v[94:95], s[2:3] op_sel_hi:[1,0]
	v_exp_f32_e32 v216, v216
	v_exp_f32_e32 v217, v217
	v_exp_f32_e32 v218, v218
	v_exp_f32_e32 v219, v219
	v_exp_f32_e32 v220, v220
	v_exp_f32_e32 v221, v221
	v_exp_f32_e32 v222, v222
	v_exp_f32_e32 v223, v223
	v_pk_add_f32 v[216:217], v[216:217], s[100:101] op_sel_hi:[1,0]
	v_pk_add_f32 v[218:219], v[218:219], s[100:101] op_sel_hi:[1,0]
	v_pk_add_f32 v[220:221], v[220:221], s[100:101] op_sel_hi:[1,0]
	v_pk_add_f32 v[222:223], v[222:223], s[100:101] op_sel_hi:[1,0]
	v_rcp_f32_e32 v216, v216
	v_rcp_f32_e32 v217, v217
	v_rcp_f32_e32 v218, v218
	v_rcp_f32_e32 v219, v219
	v_rcp_f32_e32 v220, v220
	v_rcp_f32_e32 v221, v221
	v_rcp_f32_e32 v222, v222
	v_rcp_f32_e32 v223, v223
	v_pk_mul_f32 v[100:101], v[100:101], v[216:217]
	v_pk_mul_f32 v[102:103], v[102:103], v[218:219]
	v_pk_mul_f32 v[92:93], v[92:93], v[220:221]
	v_pk_mul_f32 v[94:95], v[94:95], v[222:223]
	v_pk_mul_f32 v[100:101], v[100:101], v[96:97]
	v_pk_mul_f32 v[102:103], v[102:103], v[98:99]
	v_pk_mul_f32 v[92:93], v[92:93], v[88:89]
	v_pk_mul_f32 v[94:95], v[94:95], v[90:91]
	v_cvt_pk_bf16_f32 v236, v100, v101
	v_cvt_pk_bf16_f32 v237, v102, v103
	v_cvt_pk_bf16_f32 v238, v92, v93
	v_cvt_pk_bf16_f32 v239, v94, v95
	global_store_dwordx4 v140, v[236:239], s[4:5]
	s_add_u32 s4, s4, 0x16000
	s_addc_u32 s5, s5, 0
	v_pk_mul_f32 v[84:85], v[84:85], v[246:247] op_sel_hi:[1,0]
	v_pk_mul_f32 v[80:81], v[80:81], v[246:247] op_sel_hi:[1,0]
	v_pk_mul_f32 v[216:217], v[84:85], s[2:3] op_sel_hi:[1,0]
	v_pk_mul_f32 v[86:87], v[86:87], v[246:247] op_sel_hi:[1,0]
	v_pk_mul_f32 v[82:83], v[82:83], v[246:247] op_sel_hi:[1,0]
	v_pk_mul_f32 v[218:219], v[86:87], s[2:3] op_sel_hi:[1,0]
	v_pk_mul_f32 v[76:77], v[76:77], v[246:247] op_sel_hi:[1,0]
	v_pk_mul_f32 v[72:73], v[72:73], v[246:247] op_sel_hi:[1,0]
	v_pk_mul_f32 v[220:221], v[76:77], s[2:3] op_sel_hi:[1,0]
	v_pk_mul_f32 v[78:79], v[78:79], v[246:247] op_sel_hi:[1,0]
	v_pk_mul_f32 v[74:75], v[74:75], v[246:247] op_sel_hi:[1,0]
	v_pk_mul_f32 v[222:223], v[78:79], s[2:3] op_sel_hi:[1,0]
	v_exp_f32_e32 v216, v216
	v_exp_f32_e32 v217, v217
	v_exp_f32_e32 v218, v218
	v_exp_f32_e32 v219, v219
	v_exp_f32_e32 v220, v220
	v_exp_f32_e32 v221, v221
	v_exp_f32_e32 v222, v222
	v_exp_f32_e32 v223, v223
	v_pk_add_f32 v[216:217], v[216:217], s[100:101] op_sel_hi:[1,0]
	v_pk_add_f32 v[218:219], v[218:219], s[100:101] op_sel_hi:[1,0]
	v_pk_add_f32 v[220:221], v[220:221], s[100:101] op_sel_hi:[1,0]
	v_pk_add_f32 v[222:223], v[222:223], s[100:101] op_sel_hi:[1,0]
	v_rcp_f32_e32 v216, v216
	v_rcp_f32_e32 v217, v217
	v_rcp_f32_e32 v218, v218
	v_rcp_f32_e32 v219, v219
	v_rcp_f32_e32 v220, v220
	v_rcp_f32_e32 v221, v221
	v_rcp_f32_e32 v222, v222
	v_rcp_f32_e32 v223, v223
; __device__ __forceinline__ float sigmoidf_(float v) { return __builtin_amdgcn_rcpf(1.0f + __expf(-v)); }
; __device__ __forceinline__ u32x4 pack8(const f32x4 a, const f32x4 b) { u32x4 w; w.x = cvt_pk_bf16(a[0], a[1]); w.y = cvt_pk_bf16(a[2], a[3]); w.z = cvt_pk_bf16(b[0], b[1]); w.w = cvt_pk_bf16(b[2], b[3]); return w; }
; #define MEMFENCE asm volatile("" ::: "memory")
;     template <int KIND> __device__ __forceinline__ void run(f32x4 (&acc)[2][2][4][2], const Unit& u, int tid_in) const {
;     ...
;         if constexpr (KIND == K_FFI) { bf16_t* act = zb; float rs[8]; get_rs(u, wr, fr, rs);
; #pragma unroll
;             for (int ai = 0; ai < 2; ++ai)
; #pragma unroll
;                 for (int m = 0; m < 4; ++m) { int row = rbase + ai * 128 + m * 16; asm volatile("" : "+v"(row)); const float r = rs[ai * 4 + m]; f32x4 o[2];
; #pragma unroll
;                     for (int n = 0; n < 2; ++n) { const f32x4 g = acc[ai][0][m][n] * r, v = acc[ai][1][m][n] * r;
; #pragma unroll
;                         for (int j = 0; j < 4; ++j) o[n][j] = g[j] * sigmoidf_(g[j]) * v[j]; }
;                     *(u32x4*)(act + (size_t)row * ZW + u.pn * 128 + cl) = pack8(o[0], o[1]); MEMFENCE; }
	v_pk_mul_f32 v[84:85], v[84:85], v[216:217]
	v_pk_mul_f32 v[86:87], v[86:87], v[218:219]
	v_pk_mul_f32 v[76:77], v[76:77], v[220:221]
	v_pk_mul_f32 v[78:79], v[78:79], v[222:223]
	v_pk_mul_f32 v[84:85], v[84:85], v[80:81]
	v_pk_mul_f32 v[86:87], v[86:87], v[82:83]
	v_pk_mul_f32 v[76:77], v[76:77], v[72:73]
	v_pk_mul_f32 v[78:79], v[78:79], v[74:75]
	v_cvt_pk_bf16_f32 v236, v84, v85
	v_cvt_pk_bf16_f32 v237, v86, v87
	v_cvt_pk_bf16_f32 v238, v76, v77
	v_cvt_pk_bf16_f32 v239, v78, v79
	global_store_dwordx4 v140, v[236:239], s[4:5]
	s_add_u32 s4, s4, 0x6e000
	s_addc_u32 s5, s5, 0
	v_pk_mul_f32 v[68:69], v[68:69], v[248:249] op_sel_hi:[1,0]
	v_pk_mul_f32 v[64:65], v[64:65], v[248:249] op_sel_hi:[1,0]
	v_pk_mul_f32 v[216:217], v[68:69], s[2:3] op_sel_hi:[1,0]
	v_pk_mul_f32 v[70:71], v[70:71], v[248:249] op_sel_hi:[1,0]
	v_pk_mul_f32 v[66:67], v[66:67], v[248:249] op_sel_hi:[1,0]
	v_pk_mul_f32 v[218:219], v[70:71], s[2:3] op_sel_hi:[1,0]
	v_pk_mul_f32 v[60:61], v[60:61], v[248:249] op_sel_hi:[1,0]
	v_pk_mul_f32 v[56:57], v[56:57], v[248:249] op_sel_hi:[1,0]
	v_pk_mul_f32 v[220:221], v[60:61], s[2:3] op_sel_hi:[1,0]
	v_pk_mul_f32 v[62:63], v[62:63], v[248:249] op_sel_hi:[1,0]
	v_pk_mul_f32 v[58:59], v[58:59], v[248:249] op_sel_hi:[1,0]
	v_pk_mul_f32 v[222:223], v[62:63], s[2:3] op_sel_hi:[1,0]
	v_exp_f32_e32 v216, v216
	v_exp_f32_e32 v217, v217
	v_exp_f32_e32 v218, v218
	v_exp_f32_e32 v219, v219
	v_exp_f32_e32 v220, v220
	v_exp_f32_e32 v221, v221
	v_exp_f32_e32 v222, v222
	v_exp_f32_e32 v223, v223
	v_pk_add_f32 v[216:217], v[216:217], s[100:101] op_sel_hi:[1,0]
	v_pk_add_f32 v[218:219], v[218:219], s[100:101] op_sel_hi:[1,0]
	v_pk_add_f32 v[220:221], v[220:221], s[100:101] op_sel_hi:[1,0]
	v_pk_add_f32 v[222:223], v[222:223], s[100:101] op_sel_hi:[1,0]
	v_rcp_f32_e32 v216, v216
	v_rcp_f32_e32 v217, v217
	v_rcp_f32_e32 v218, v218
	v_rcp_f32_e32 v219, v219
	v_rcp_f32_e32 v220, v220
	v_rcp_f32_e32 v221, v221
	v_rcp_f32_e32 v222, v222
	v_rcp_f32_e32 v223, v223
	v_pk_mul_f32 v[68:69], v[68:69], v[216:217]
	v_pk_mul_f32 v[70:71], v[70:71], v[218:219]
	v_pk_mul_f32 v[60:61], v[60:61], v[220:221]
	v_pk_mul_f32 v[62:63], v[62:63], v[222:223]
	v_pk_mul_f32 v[68:69], v[68:69], v[64:65]
	v_pk_mul_f32 v[70:71], v[70:71], v[66:67]
	v_pk_mul_f32 v[60:61], v[60:61], v[56:57]
	v_pk_mul_f32 v[62:63], v[62:63], v[58:59]
	v_cvt_pk_bf16_f32 v236, v68, v69
	v_cvt_pk_bf16_f32 v237, v70, v71
	v_cvt_pk_bf16_f32 v238, v60, v61
	v_cvt_pk_bf16_f32 v239, v62, v63
	global_store_dwordx4 v140, v[236:239], s[4:5]
	s_add_u32 s4, s4, 0x16000
	s_addc_u32 s5, s5, 0
	v_pk_mul_f32 v[52:53], v[52:53], v[250:251] op_sel_hi:[1,0]
	v_pk_mul_f32 v[48:49], v[48:49], v[250:251] op_sel_hi:[1,0]
	v_pk_mul_f32 v[216:217], v[52:53], s[2:3] op_sel_hi:[1,0]
	v_pk_mul_f32 v[54:55], v[54:55], v[250:251] op_sel_hi:[1,0]
	v_pk_mul_f32 v[50:51], v[50:51], v[250:251] op_sel_hi:[1,0]
	v_pk_mul_f32 v[218:219], v[54:55], s[2:3] op_sel_hi:[1,0]
	v_pk_mul_f32 v[44:45], v[44:45], v[250:251] op_sel_hi:[1,0]
	v_pk_mul_f32 v[40:41], v[40:41], v[250:251] op_sel_hi:[1,0]
	v_pk_mul_f32 v[220:221], v[44:45], s[2:3] op_sel_hi:[1,0]
	v_pk_mul_f32 v[46:47], v[46:47], v[250:251] op_sel_hi:[1,0]
	v_pk_mul_f32 v[42:43], v[42:43], v[250:251] op_sel_hi:[1,0]
	v_pk_mul_f32 v[222:223], v[46:47], s[2:3] op_sel_hi:[1,0]
	v_exp_f32_e32 v216, v216
	v_exp_f32_e32 v217, v217
	v_exp_f32_e32 v218, v218
	v_exp_f32_e32 v219, v219
	v_exp_f32_e32 v220, v220
	v_exp_f32_e32 v221, v221
	v_exp_f32_e32 v222, v222
	v_exp_f32_e32 v223, v223
	v_pk_add_f32 v[216:217], v[216:217], s[100:101] op_sel_hi:[1,0]
	v_pk_add_f32 v[218:219], v[218:219], s[100:101] op_sel_hi:[1,0]
	v_pk_add_f32 v[220:221], v[220:221], s[100:101] op_sel_hi:[1,0]
	v_pk_add_f32 v[222:223], v[222:223], s[100:101] op_sel_hi:[1,0]
	v_rcp_f32_e32 v216, v216
	v_rcp_f32_e32 v217, v217
	v_rcp_f32_e32 v218, v218
	v_rcp_f32_e32 v219, v219
	v_rcp_f32_e32 v220, v220
	v_rcp_f32_e32 v221, v221
	v_rcp_f32_e32 v222, v222
	v_rcp_f32_e32 v223, v223
	v_pk_mul_f32 v[52:53], v[52:53], v[216:217]
	v_pk_mul_f32 v[54:55], v[54:55], v[218:219]
	v_pk_mul_f32 v[44:45], v[44:45], v[220:221]
	v_pk_mul_f32 v[46:47], v[46:47], v[222:223]
	v_pk_mul_f32 v[52:53], v[52:53], v[48:49]
	v_pk_mul_f32 v[54:55], v[54:55], v[50:51]
	v_pk_mul_f32 v[44:45], v[44:45], v[40:41]
	v_pk_mul_f32 v[46:47], v[46:47], v[42:43]
	v_cvt_pk_bf16_f32 v236, v52, v53
; __device__ __forceinline__ float sigmoidf_(float v) { return __builtin_amdgcn_rcpf(1.0f + __expf(-v)); }
; __device__ __forceinline__ u32x4 pack8(const f32x4 a, const f32x4 b) { u32x4 w; w.x = cvt_pk_bf16(a[0], a[1]); w.y = cvt_pk_bf16(a[2], a[3]); w.z = cvt_pk_bf16(b[0], b[1]); w.w = cvt_pk_bf16(b[2], b[3]); return w; }
; #define MEMFENCE asm volatile("" ::: "memory")
; #define G_WAIT_V(n) asm volatile("s_waitcnt vmcnt(" #n ")" ::: "memory")
; #define G_BAR __builtin_amdgcn_s_barrier()
;     template <int KIND> __device__ __forceinline__ void run(f32x4 (&acc)[2][2][4][2], const Unit& u, int tid_in) const {
;     ...
;         if constexpr (KIND == K_FFI) { bf16_t* act = zb; float rs[8]; get_rs(u, wr, fr, rs);
; #pragma unroll
;             for (int ai = 0; ai < 2; ++ai)
; #pragma unroll
;                 for (int m = 0; m < 4; ++m) { int row = rbase + ai * 128 + m * 16; asm volatile("" : "+v"(row)); const float r = rs[ai * 4 + m]; f32x4 o[2];
; #pragma unroll
;                     for (int n = 0; n < 2; ++n) { const f32x4 g = acc[ai][0][m][n] * r, v = acc[ai][1][m][n] * r;
; #pragma unroll
;                         for (int j = 0; j < 4; ++j) o[n][j] = g[j] * sigmoidf_(g[j]) * v[j]; }
;                     *(u32x4*)(act + (size_t)row * ZW + u.pn * 128 + cl) = pack8(o[0], o[1]); MEMFENCE; }
;     ...
;         if (!has_next) break;
;         if (!(cs.kind == K_MG_B && cur.aux < 2))
; #pragma unroll
;         for (int a = 0; a < 2; ++a)
; #pragma unroll
;             for (int b = 0; b < 2; ++b)
; #pragma unroll
;                 for (int m = 0; m < 4; ++m)
; #pragma unroll
;                     for (int n = 0; n < 2; ++n) acc[a][b][m][n] = (f32x4){0.f, 0.f, 0.f, 0.f};
;         cur = nxt; cA = nA; cB = nB; ++ui;
;     }
;     G_WAIT_V(0);
;     if (wr == 0) G_BAR;
;     G_BAR;
	v_cvt_pk_bf16_f32 v237, v54, v55
	v_cvt_pk_bf16_f32 v238, v44, v45
	v_cvt_pk_bf16_f32 v239, v46, v47
	global_store_dwordx4 v140, v[236:239], s[4:5]
	s_add_u32 s4, s4, 0x16000
	s_addc_u32 s5, s5, 0
	v_pk_mul_f32 v[36:37], v[36:37], v[252:253] op_sel_hi:[1,0]
	v_pk_mul_f32 v[32:33], v[32:33], v[252:253] op_sel_hi:[1,0]
	v_pk_mul_f32 v[216:217], v[36:37], s[2:3] op_sel_hi:[1,0]
	v_pk_mul_f32 v[38:39], v[38:39], v[252:253] op_sel_hi:[1,0]
	v_pk_mul_f32 v[34:35], v[34:35], v[252:253] op_sel_hi:[1,0]
	v_pk_mul_f32 v[218:219], v[38:39], s[2:3] op_sel_hi:[1,0]
	v_pk_mul_f32 v[28:29], v[28:29], v[252:253] op_sel_hi:[1,0]
	v_pk_mul_f32 v[24:25], v[24:25], v[252:253] op_sel_hi:[1,0]
	v_pk_mul_f32 v[220:221], v[28:29], s[2:3] op_sel_hi:[1,0]
	v_pk_mul_f32 v[30:31], v[30:31], v[252:253] op_sel_hi:[1,0]
	v_pk_mul_f32 v[26:27], v[26:27], v[252:253] op_sel_hi:[1,0]
	v_pk_mul_f32 v[222:223], v[30:31], s[2:3] op_sel_hi:[1,0]
	v_exp_f32_e32 v216, v216
	v_exp_f32_e32 v217, v217
	v_exp_f32_e32 v218, v218
	v_exp_f32_e32 v219, v219
	v_exp_f32_e32 v220, v220
	v_exp_f32_e32 v221, v221
	v_exp_f32_e32 v222, v222
	v_exp_f32_e32 v223, v223
	v_pk_add_f32 v[216:217], v[216:217], s[100:101] op_sel_hi:[1,0]
	v_pk_add_f32 v[218:219], v[218:219], s[100:101] op_sel_hi:[1,0]
	v_pk_add_f32 v[220:221], v[220:221], s[100:101] op_sel_hi:[1,0]
	v_pk_add_f32 v[222:223], v[222:223], s[100:101] op_sel_hi:[1,0]
	v_rcp_f32_e32 v216, v216
	v_rcp_f32_e32 v217, v217
	v_rcp_f32_e32 v218, v218
	v_rcp_f32_e32 v219, v219
	v_rcp_f32_e32 v220, v220
	v_rcp_f32_e32 v221, v221
	v_rcp_f32_e32 v222, v222
	v_rcp_f32_e32 v223, v223
	v_pk_mul_f32 v[36:37], v[36:37], v[216:217]
	v_pk_mul_f32 v[38:39], v[38:39], v[218:219]
	v_pk_mul_f32 v[28:29], v[28:29], v[220:221]
	v_pk_mul_f32 v[30:31], v[30:31], v[222:223]
	v_pk_mul_f32 v[36:37], v[36:37], v[32:33]
	v_pk_mul_f32 v[38:39], v[38:39], v[34:35]
	v_pk_mul_f32 v[28:29], v[28:29], v[24:25]
	v_pk_mul_f32 v[30:31], v[30:31], v[26:27]
	v_cvt_pk_bf16_f32 v236, v36, v37
	v_cvt_pk_bf16_f32 v237, v38, v39
	v_cvt_pk_bf16_f32 v238, v28, v29
	v_cvt_pk_bf16_f32 v239, v30, v31
	global_store_dwordx4 v140, v[236:239], s[4:5]
	s_add_u32 s4, s4, 0x16000
	s_addc_u32 s5, s5, 0
	v_pk_mul_f32 v[20:21], v[20:21], v[254:255] op_sel_hi:[1,0]
	v_pk_mul_f32 v[16:17], v[16:17], v[254:255] op_sel_hi:[1,0]
	v_pk_mul_f32 v[216:217], v[20:21], s[2:3] op_sel_hi:[1,0]
	v_pk_mul_f32 v[22:23], v[22:23], v[254:255] op_sel_hi:[1,0]
	v_pk_mul_f32 v[18:19], v[18:19], v[254:255] op_sel_hi:[1,0]
	v_pk_mul_f32 v[218:219], v[22:23], s[2:3] op_sel_hi:[1,0]
	v_pk_mul_f32 v[12:13], v[12:13], v[254:255] op_sel_hi:[1,0]
	v_pk_mul_f32 v[8:9], v[8:9], v[254:255] op_sel_hi:[1,0]
	v_pk_mul_f32 v[220:221], v[12:13], s[2:3] op_sel_hi:[1,0]
	v_pk_mul_f32 v[14:15], v[14:15], v[254:255] op_sel_hi:[1,0]
	v_pk_mul_f32 v[10:11], v[10:11], v[254:255] op_sel_hi:[1,0]
	v_pk_mul_f32 v[222:223], v[14:15], s[2:3] op_sel_hi:[1,0]
	v_exp_f32_e32 v216, v216
	v_exp_f32_e32 v217, v217
	v_exp_f32_e32 v218, v218
	v_exp_f32_e32 v219, v219
	v_exp_f32_e32 v220, v220
	v_exp_f32_e32 v221, v221
	v_exp_f32_e32 v222, v222
	v_exp_f32_e32 v223, v223
	v_pk_add_f32 v[216:217], v[216:217], s[100:101] op_sel_hi:[1,0]
	v_pk_add_f32 v[218:219], v[218:219], s[100:101] op_sel_hi:[1,0]
	v_pk_add_f32 v[220:221], v[220:221], s[100:101] op_sel_hi:[1,0]
	v_pk_add_f32 v[222:223], v[222:223], s[100:101] op_sel_hi:[1,0]
	v_rcp_f32_e32 v216, v216
	v_rcp_f32_e32 v217, v217
	v_rcp_f32_e32 v218, v218
	v_rcp_f32_e32 v219, v219
	v_rcp_f32_e32 v220, v220
	v_rcp_f32_e32 v221, v221
	v_rcp_f32_e32 v222, v222
	v_rcp_f32_e32 v223, v223
	v_pk_mul_f32 v[20:21], v[20:21], v[216:217]
	v_pk_mul_f32 v[22:23], v[22:23], v[218:219]
	v_pk_mul_f32 v[12:13], v[12:13], v[220:221]
	v_pk_mul_f32 v[14:15], v[14:15], v[222:223]
	v_pk_mul_f32 v[20:21], v[20:21], v[16:17]
	v_pk_mul_f32 v[22:23], v[22:23], v[18:19]
	v_pk_mul_f32 v[12:13], v[12:13], v[8:9]
	v_pk_mul_f32 v[14:15], v[14:15], v[10:11]
	v_cvt_pk_bf16_f32 v236, v20, v21
	v_cvt_pk_bf16_f32 v237, v22, v23
	v_cvt_pk_bf16_f32 v238, v12, v13
	v_cvt_pk_bf16_f32 v239, v14, v15
	global_store_dwordx4 v140, v[236:239], s[4:5]
	s_mov_b32 s38, s11
	s_mov_b32 s37, s10
	s_mov_b64 s[18:19], s[14:15]
	s_mov_b64 s[16:17], s[12:13]
	s_mov_b32 s33, s36
	s_and_b64 vcc, exec, s[8:9]
	s_cbranch_vccz .LBB0_1115
	s_waitcnt vmcnt(0)
	s_cmpk_gt_u32 s20, 0xff
	s_cbranch_scc1 .LBB0_1124
	s_barrier
